# phase-0 activation cast + first RMSNorm loop: all 8 row loads issued together with counted waits 5/2/0 instead of three full drains (temps renamed)
# speedup vs baseline: 1.0075x; 1.0019x over previous
; __device__ __forceinline__ unsigned pk2(float lo, float hi) { const f32v2_t v = {lo, hi}; return __builtin_bit_cast(unsigned, __builtin_convertvector(v, bf16v2_t)); }
; __device__ __forceinline__ float shx(float v, int mask, int lane) { return __int_as_float(__builtin_amdgcn_ds_bpermute((lane ^ mask) << 2, __float_as_int(v))); }
; __device__ __forceinline__ void norm_phase(const float* __restrict__ xin, const float* __restrict__ gain, const float* __restrict__ shift, const float* __restrict__ scale, bf16_t* __restrict__ H) {
;     ...
;     for (int row = gw; row < T; row += nw) {
;         const float* xr = xin + (size_t)row * D;
;         f32x4 v[8]; float ss = 0.f;
; #pragma unroll
;         for (int i = 0; i < 8; ++i) { v[i] = *(const f32x4*)(xr + i * 256 + lane * 4); ss += v[i][0] * v[i][0] + v[i][1] * v[i][1] + v[i][2] * v[i][2] + v[i][3] * v[i][3]; }
; #pragma unroll
;         for (int o = 32; o > 0; o >>= 1) ss += shx(ss, o, lane);
;         const float inv = rsqrtf(ss * (1.f / D) + EPS);
; #pragma unroll
;         for (int i = 0; i < 8; ++i) {
;             const int c = i * 256 + lane * 4;
;             const f32x4 g = *(const f32x4*)(gain + c), sh = *(const f32x4*)(shift + c), sc = *(const f32x4*)(scale + c);
;             const f32x4 y = v[i] * inv * g * (1.f + sc) + sh;
;             u32x2 o = {pk2(y[0], y[1]), pk2(y[2], y[3])};
;             *(u32x2*)(H + (size_t)row * D + c) = o;
;         }
;     }
.LBB0_39:
	v_lshl_add_u64 v[78:79], s[26:27], 0, v[128:129]
	v_add_co_u32_e32 v66, vcc, 0x11218000, v78
	s_mov_b32 s4, 0x11219000
	s_nop 0
	v_addc_co_u32_e32 v67, vcc, 0, v79, vcc
	flat_load_dwordx4 v[140:143], v[66:67]
	flat_load_dwordx4 v[74:77], v[66:67] offset:1024
	flat_load_dwordx4 v[70:73], v[66:67] offset:2048
	v_add_co_u32_e32 v78, vcc, s4, v78
	s_mov_b32 s4, 0x15218000
	s_nop 0
	v_addc_co_u32_e32 v79, vcc, 0, v79, vcc
	flat_load_dwordx4 v[66:69], v[66:67] offset:3072
	s_nop 0
	flat_load_dwordx4 v[90:93], v[78:79]
	flat_load_dwordx4 v[82:85], v[78:79] offset:1024
	flat_load_dwordx4 v[86:89], v[78:79] offset:2048
	s_nop 0
	flat_load_dwordx4 v[78:81], v[78:79] offset:3072
	v_add_u32_e32 v132, s88, v132
	v_lshl_add_u64 v[128:129], v[128:129], 0, s[12:13]
	s_waitcnt vmcnt(5)
	v_mul_f32_e32 v0, v141, v141
	v_mul_f32_e32 v144, v75, v75
	v_fmac_f32_e32 v0, v140, v140
	v_fmac_f32_e32 v144, v74, v74
	v_fmac_f32_e32 v0, v142, v142
	v_fmac_f32_e32 v144, v76, v76
	v_fmac_f32_e32 v0, v143, v143
	v_fmac_f32_e32 v144, v77, v77
	v_add_f32_e32 v0, v0, v144
	v_mul_f32_e32 v144, v71, v71
	v_fmac_f32_e32 v144, v70, v70
	v_fmac_f32_e32 v144, v72, v72
	v_fmac_f32_e32 v144, v73, v73
	v_add_f32_e32 v0, v0, v144
	s_waitcnt vmcnt(2)
	v_mov_b32_e32 v144, v91
	v_mul_f32_e32 v130, v67, v67
	v_fmac_f32_e32 v130, v66, v66
	v_fmac_f32_e32 v130, v68, v68
	v_fmac_f32_e32 v130, v69, v69
	v_mov_b32_e32 v145, v83
	v_add_f32_e32 v0, v0, v130
	v_mov_b32_e32 v130, v90
	v_mov_b32_e32 v131, v82
	v_pk_mul_f32 v[144:145], v[144:145], v[144:145]
	s_nop 0
	v_pk_fma_f32 v[130:131], v[130:131], v[130:131], v[144:145]
	v_mov_b32_e32 v144, v92
	v_mov_b32_e32 v145, v84
	v_pk_fma_f32 v[130:131], v[144:145], v[144:145], v[130:131]
	v_mov_b32_e32 v144, v93
	v_mov_b32_e32 v145, v85
	v_pk_fma_f32 v[130:131], v[144:145], v[144:145], v[130:131]
	s_nop 0
	v_add_f32_e32 v0, v0, v130
	v_add_f32_e32 v0, v0, v131
	s_waitcnt vmcnt(0) lgkmcnt(0)
	v_mov_b32_e32 v144, v87
	v_mov_b32_e32 v145, v79
	v_mov_b32_e32 v130, v86
	v_mov_b32_e32 v131, v78
	v_pk_mul_f32 v[144:145], v[144:145], v[144:145]
	s_nop 0
	v_pk_fma_f32 v[130:131], v[130:131], v[130:131], v[144:145]
	v_mov_b32_e32 v144, v88
	v_mov_b32_e32 v145, v80
	v_pk_fma_f32 v[130:131], v[144:145], v[144:145], v[130:131]
	v_mov_b32_e32 v144, v89
	v_mov_b32_e32 v145, v81
	v_pk_fma_f32 v[130:131], v[144:145], v[144:145], v[130:131]
	s_nop 0
	v_add_f32_e32 v0, v0, v130
	v_add_f32_e32 v0, v0, v131
	ds_bpermute_b32 v130, v133, v0
	s_waitcnt lgkmcnt(0)
	v_add_f32_e32 v0, v0, v130
	ds_bpermute_b32 v130, v134, v0
	s_waitcnt lgkmcnt(0)
	v_add_f32_e32 v0, v0, v130
	ds_bpermute_b32 v130, v135, v0
	s_waitcnt lgkmcnt(0)
	v_add_f32_e32 v0, v0, v130
	ds_bpermute_b32 v130, v136, v0
	s_waitcnt lgkmcnt(0)
	v_add_f32_e32 v0, v0, v130
	ds_bpermute_b32 v130, v137, v0
	s_waitcnt lgkmcnt(0)
	v_add_f32_e32 v0, v0, v130
	ds_bpermute_b32 v130, v138, v0
	s_waitcnt lgkmcnt(0)
	v_add_f32_e32 v0, v0, v130
	v_fmamk_f32 v0, v0, 0x3a000000, v184
	v_cmp_gt_f32_e32 vcc, s90, v0
	v_mul_f32_e32 v130, 0x4b800000, v0
	s_nop 0
	v_cndmask_b32_e32 v0, v0, v130, vcc
	v_rsq_f32_e32 v0, v0
	s_nop 0
	v_mul_f32_e32 v130, 0x45800000, v0
	v_cndmask_b32_e32 v0, v0, v130, vcc
	v_pk_mul_f32 v[130:131], v[142:143], v[0:1] op_sel_hi:[1,0]
	v_pk_mul_f32 v[140:141], v[140:141], v[0:1] op_sel_hi:[1,0]
	v_pk_mul_f32 v[130:131], v[8:9], v[130:131]
	v_pk_mul_f32 v[140:141], v[6:7], v[140:141]
	v_pk_mul_f32 v[68:69], v[68:69], v[0:1] op_sel_hi:[1,0]
	v_pk_mul_f32 v[66:67], v[66:67], v[0:1] op_sel_hi:[1,0]
	v_pk_fma_f32 v[142:143], v[96:97], v[130:131], v[4:5]
	v_pk_fma_f32 v[130:131], v[98:99], v[140:141], v[2:3]
	v_lshl_add_u64 v[140:141], s[26:27], 0, v[94:95]
	v_pk_mul_f32 v[66:67], v[26:27], v[66:67]
	v_pk_mul_f32 v[68:69], v[28:29], v[68:69]
	v_add_co_u32_e32 v140, vcc, s4, v140
	v_pk_fma_f32 v[68:69], v[108:109], v[68:69], v[32:33]
	v_pk_fma_f32 v[66:67], v[110:111], v[66:67], v[30:31]
	v_addc_co_u32_e32 v141, vcc, 0, v141, vcc
	v_cvt_pk_bf16_f32 v66, v66, v67
	v_cvt_pk_bf16_f32 v67, v68, v69
	flat_store_dwordx2 v[140:141], v[66:67] offset:1536
	v_pk_mul_f32 v[66:67], v[92:93], v[0:1] op_sel_hi:[1,0]
	v_pk_mul_f32 v[68:69], v[90:91], v[0:1] op_sel_hi:[1,0]
	v_pk_mul_f32 v[66:67], v[48:49], v[66:67]
	v_pk_mul_f32 v[68:69], v[46:47], v[68:69]
	v_pk_fma_f32 v[66:67], v[112:113], v[66:67], v[36:37]
	v_pk_fma_f32 v[68:69], v[114:115], v[68:69], v[34:35]
	v_pk_mul_f32 v[76:77], v[76:77], v[0:1] op_sel_hi:[1,0]
	v_cvt_pk_bf16_f32 v68, v68, v69
	v_cvt_pk_bf16_f32 v69, v66, v67
	flat_store_dwordx2 v[140:141], v[68:69] offset:2048
	v_pk_mul_f32 v[66:67], v[84:85], v[0:1] op_sel_hi:[1,0]
	v_pk_mul_f32 v[68:69], v[82:83], v[0:1] op_sel_hi:[1,0]
	v_pk_mul_f32 v[66:67], v[52:53], v[66:67]
	v_pk_mul_f32 v[68:69], v[50:51], v[68:69]
	v_pk_fma_f32 v[66:67], v[116:117], v[66:67], v[40:41]
	v_pk_fma_f32 v[68:69], v[118:119], v[68:69], v[38:39]
	v_pk_mul_f32 v[74:75], v[74:75], v[0:1] op_sel_hi:[1,0]
	v_cvt_pk_bf16_f32 v68, v68, v69
	v_cvt_pk_bf16_f32 v69, v66, v67
	flat_store_dwordx2 v[140:141], v[68:69] offset:2560
	v_pk_mul_f32 v[66:67], v[88:89], v[0:1] op_sel_hi:[1,0]
	v_pk_mul_f32 v[68:69], v[86:87], v[0:1] op_sel_hi:[1,0]
	v_pk_mul_f32 v[66:67], v[56:57], v[66:67]
	v_pk_mul_f32 v[68:69], v[54:55], v[68:69]
	v_pk_fma_f32 v[66:67], v[120:121], v[66:67], v[44:45]
	v_pk_fma_f32 v[68:69], v[122:123], v[68:69], v[42:43]
	v_pk_mul_f32 v[72:73], v[72:73], v[0:1] op_sel_hi:[1,0]
	v_cvt_pk_bf16_f32 v68, v68, v69
	v_cvt_pk_bf16_f32 v69, v66, v67
	v_pk_mul_f32 v[70:71], v[70:71], v[0:1] op_sel_hi:[1,0]
	flat_store_dwordx2 v[140:141], v[68:69] offset:3072
	v_pk_mul_f32 v[66:67], v[80:81], v[0:1] op_sel_hi:[1,0]
	v_pk_mul_f32 v[68:69], v[78:79], v[0:1] op_sel_hi:[1,0]
	v_pk_mul_f32 v[74:75], v[10:11], v[74:75]
	v_pk_mul_f32 v[76:77], v[12:13], v[76:77]
	v_pk_mul_f32 v[70:71], v[22:23], v[70:71]
	v_pk_mul_f32 v[72:73], v[24:25], v[72:73]
	v_pk_mul_f32 v[68:69], v[58:59], v[68:69]
	v_pk_mul_f32 v[66:67], v[60:61], v[66:67]
	v_pk_fma_f32 v[76:77], v[100:101], v[76:77], v[16:17]
	v_pk_fma_f32 v[74:75], v[102:103], v[74:75], v[14:15]
	v_pk_fma_f32 v[72:73], v[104:105], v[72:73], v[20:21]
	v_pk_fma_f32 v[70:71], v[106:107], v[70:71], v[18:19]
	v_pk_fma_f32 v[66:67], v[124:125], v[66:67], v[64:65]
	v_pk_fma_f32 v[68:69], v[126:127], v[68:69], v[62:63]
	v_cmp_lt_i32_e32 vcc, s91, v132
	v_cvt_pk_bf16_f32 v130, v130, v131
	v_cvt_pk_bf16_f32 v131, v142, v143
	v_cvt_pk_bf16_f32 v74, v74, v75
	v_cvt_pk_bf16_f32 v75, v76, v77
	v_cvt_pk_bf16_f32 v70, v70, v71
	v_cvt_pk_bf16_f32 v71, v72, v73
	v_cvt_pk_bf16_f32 v68, v68, v69
	v_cvt_pk_bf16_f32 v69, v66, v67
	v_lshl_add_u64 v[94:95], v[94:95], 0, s[10:11]
	s_or_b64 s[2:3], vcc, s[2:3]
	flat_store_dwordx2 v[140:141], v[130:131]
	flat_store_dwordx2 v[140:141], v[74:75] offset:512
	flat_store_dwordx2 v[140:141], v[70:71] offset:1024
	flat_store_dwordx2 v[140:141], v[68:69] offset:3584
	s_andn2_b64 exec, exec, s[2:3]
	s_cbranch_execnz .LBB0_39
